# next DF unit's Q lines touched by wave 0 right after the claim is folded (wave index from its spill lane this time), gate waits counted around the four touches
# speedup vs baseline: 1.0090x; 1.0001x over previous
.LBB0_460:
	s_waitcnt lgkmcnt(0)
	s_barrier
	s_and_b64 vcc, exec, s[4:5]
	s_cbranch_vccnz .LBB0_299
	v_mov_b32_e32 v2, v217
	s_nop 1
	v_permlane32_swap_b32_e32 v217, v2
	v_add_f32_e32 v2, v217, v2
	v_div_scale_f32 v3, s[2:3], v2, v2, 1.0
	v_rcp_f32_e32 v4, v3
	s_waitcnt vmcnt(3)
	v_min_u32_e32 v253, 0xffff, v253
	v_or_b32_e32 v95, v95, v253
	s_mov_b64 s[24:25], 0
	v_readlane_b32 s21, v255, 10
	s_cmp_lg_u32 s21, 0
	s_cbranch_scc1 .Lqpf_end
	v_readfirstlane_b32 s21, v95
	s_lshr_b32 s22, s21, 16
	s_and_b32 s21, s21, 0xffff
	s_cmp_gt_u32 s22, 7
	s_cbranch_scc1 .Lqpf_end
	s_cmp_gt_u32 s21, 63
	s_cbranch_scc1 .Lqpf_end
	s_bfe_u32 s23, s21, 0x40001
	s_xor_b32 s23, s23, 15
	s_lshr_b32 s26, s21, 4
	s_and_b32 s26, s26, 2
	s_and_b32 s27, s21, 1
	s_or_b32 s26, s26, s27
	s_xor_b32 s26, s26, 2
	s_lshl_b32 s27, s22, 21
	s_lshl_b32 s26, s26, 19
	s_add_u32 s27, s27, s26
	s_lshl_b32 s23, s23, 15
	s_add_u32 s27, s27, s23
	s_add_u32 s27, s27, 0x4000000
	s_add_u32 s28, s78, s27
	s_addc_u32 s29, s79, 0
	v_lshlrev_b32_e32 v252, 7, v231
	global_load_dword v253, v252, s[28:29]
	v_add_u32_e32 v252, 0x2000, v252
	global_load_dword v253, v252, s[28:29]
	v_add_u32_e32 v252, 0x2000, v252
	global_load_dword v253, v252, s[28:29]
	v_add_u32_e32 v252, 0x2000, v252
	global_load_dword v253, v252, s[28:29]
	s_mov_b64 s[24:25], -1
